# GEMM K-loop header pinned with .p2align to the baseline's 64-byte offset (the hipcc loop loses up to 60 us when upstream edits shift it by 4 bytes)
# speedup vs baseline: 1.0207x; 1.0011x over previous
; #define PG8_STAGE(bufoff, gbase, voff) do { _Pragma("unroll") for (int _i = 0; _i < 2; ++_i) \
;         __builtin_amdgcn_global_load_lds((const unsigned*)((const char*)(gbase) + (voff)[_i]), (LAS unsigned*)(lds + (bufoff) + ldsw + _i * 8192), 16, 0, 0); } while (0)
; #define PG8_WAIT_V(n) asm volatile("s_waitcnt vmcnt(" #n ")" ::: "memory")
; #define PG8_BAR __builtin_amdgcn_s_barrier()
; #define PG8_UA(u) unit_a(jt, (u), tstep)
; #define PG8_UB(u) unit_b(jt, (u), tstep)
; __device__ __forceinline__ void gemm_phase(LAS unsigned char* lds, const LAS unsigned char* jt, const int K, const int n0, const int n1, const int G, const int c) {
;     ...
;     f32x4 acc[2][2][4][2];
; #pragma unroll
;     for (int a = 0; a < 2; ++a)
; #pragma unroll
;         for (int b = 0; b < 2; ++b)
; #pragma unroll
;             for (int m = 0; m < 4; ++m)
; #pragma unroll
;                 for (int n = 0; n < 2; ++n) acc[a][b][m][n] = (f32x4){0.f, 0.f, 0.f, 0.f};
;     bf16x8 At[4][2], B0[2][2], B1[2][2];
;     const char* cA = PG8_UA(cur); const char* cB = PG8_UB(cur);
;     PG8_STAGE(PG8_SB(0, 0), cB, voffB); PG8_STAGE(PG8_SB(0, 1), cB + hstep, voffB); PG8_STAGE(PG8_SA(0, 0), cA, voffA); PG8_STAGE(PG8_SA(0, 1), cA + hstep, voffA);
;     if (wr == 1) PG8_BAR;
;     PG8_WAIT_V(2); PG8_BAR;
;     PG8_STAGE(PG8_SB(1, 0), cB + kstep, voffB); PG8_STAGE(PG8_SA(1, 0), cA + kstep, voffA); PG8_STAGE(PG8_SB(1, 1), cB + hstep + kstep, voffB);
;     PG8_WAIT_V(6); PG8_BAR;
;     for (;;) {
;         const bool has_next = next_unit(ui + 1, G, c, jt, n0, n1, nxt);
;         const char* nA = cA; const char* nB = cB;
;         if (has_next) { nA = PG8_UA(nxt); nB = PG8_UB(nxt); }
;         for (int t = 0; t < nt; t += 2) {
.LBB0_293:
	s_andn2_b64 vcc, exec, s[28:29]
	s_cbranch_vccnz .LBB0_301
	s_add_u32 s14, s0, 0x100
	s_addc_u32 s15, s1, 0
	s_add_u32 s0, s12, 0x80
	v_mov_b32_e32 v0, 0
	s_addc_u32 s1, s13, 0
	s_mov_b32 s12, 0
	v_mov_b32_e32 v1, v0
	v_mov_b32_e32 v2, v0
	v_mov_b32_e32 v3, v0
	v_mov_b32_e32 v4, v0
	v_mov_b32_e32 v5, v0
	v_mov_b32_e32 v6, v0
	v_mov_b32_e32 v7, v0
	v_mov_b32_e32 v16, v0
	v_mov_b32_e32 v17, v0
	v_mov_b32_e32 v18, v0
	v_mov_b32_e32 v19, v0
	v_mov_b32_e32 v20, v0
	v_mov_b32_e32 v21, v0
	v_mov_b32_e32 v22, v0
	v_mov_b32_e32 v23, v0
	v_mov_b32_e32 v32, v0
	v_mov_b32_e32 v33, v0
	v_mov_b32_e32 v34, v0
	v_mov_b32_e32 v35, v0
	v_mov_b32_e32 v36, v0
	v_mov_b32_e32 v37, v0
	v_mov_b32_e32 v38, v0
	v_mov_b32_e32 v39, v0
	v_mov_b32_e32 v48, v0
	v_mov_b32_e32 v49, v0
	v_mov_b32_e32 v50, v0
	v_mov_b32_e32 v51, v0
	v_mov_b32_e32 v52, v0
	v_mov_b32_e32 v53, v0
	v_mov_b32_e32 v54, v0
	v_mov_b32_e32 v55, v0
	v_mov_b32_e32 v8, v0
	v_mov_b32_e32 v9, v0
	v_mov_b32_e32 v10, v0
	v_mov_b32_e32 v11, v0
	v_mov_b32_e32 v12, v0
	v_mov_b32_e32 v13, v0
	v_mov_b32_e32 v14, v0
	v_mov_b32_e32 v15, v0
	v_mov_b32_e32 v24, v0
	v_mov_b32_e32 v25, v0
	v_mov_b32_e32 v26, v0
	v_mov_b32_e32 v27, v0
	v_mov_b32_e32 v28, v0
	v_mov_b32_e32 v29, v0
	v_mov_b32_e32 v30, v0
	v_mov_b32_e32 v31, v0
	v_mov_b32_e32 v40, v0
	v_mov_b32_e32 v41, v0
	v_mov_b32_e32 v42, v0
	v_mov_b32_e32 v43, v0
	v_mov_b32_e32 v44, v0
	v_mov_b32_e32 v45, v0
	v_mov_b32_e32 v46, v0
	v_mov_b32_e32 v47, v0
	v_mov_b32_e32 v56, v0
	v_mov_b32_e32 v57, v0
	v_mov_b32_e32 v58, v0
	v_mov_b32_e32 v59, v0
	v_mov_b32_e32 v60, v0
	v_mov_b32_e32 v61, v0
	v_mov_b32_e32 v62, v0
	v_mov_b32_e32 v63, v0
	v_mov_b32_e32 v64, v0
	v_mov_b32_e32 v65, v0
	v_mov_b32_e32 v66, v0
	v_mov_b32_e32 v67, v0
	v_mov_b32_e32 v68, v0
	v_mov_b32_e32 v69, v0
	v_mov_b32_e32 v70, v0
	v_mov_b32_e32 v71, v0
	v_mov_b32_e32 v80, v0
	v_mov_b32_e32 v81, v0
	v_mov_b32_e32 v82, v0
	v_mov_b32_e32 v83, v0
	v_mov_b32_e32 v84, v0
	v_mov_b32_e32 v85, v0
	v_mov_b32_e32 v86, v0
	v_mov_b32_e32 v87, v0
	v_mov_b32_e32 v100, v0
	v_mov_b32_e32 v101, v0
	v_mov_b32_e32 v102, v0
	v_mov_b32_e32 v103, v0
	v_mov_b32_e32 v104, v0
	v_mov_b32_e32 v105, v0
	v_mov_b32_e32 v106, v0
	v_mov_b32_e32 v107, v0
	v_mov_b32_e32 v116, v0
	v_mov_b32_e32 v117, v0
	v_mov_b32_e32 v118, v0
	v_mov_b32_e32 v119, v0
	v_mov_b32_e32 v120, v0
	v_mov_b32_e32 v121, v0
	v_mov_b32_e32 v122, v0
	v_mov_b32_e32 v123, v0
	v_mov_b32_e32 v72, v0
	v_mov_b32_e32 v73, v0
	v_mov_b32_e32 v74, v0
	v_mov_b32_e32 v75, v0
	v_mov_b32_e32 v76, v0
	v_mov_b32_e32 v77, v0
	v_mov_b32_e32 v78, v0
	v_mov_b32_e32 v79, v0
	v_mov_b32_e32 v88, v0
	v_mov_b32_e32 v89, v0
	v_mov_b32_e32 v90, v0
	v_mov_b32_e32 v91, v0
	v_mov_b32_e32 v92, v0
	v_mov_b32_e32 v93, v0
	v_mov_b32_e32 v94, v0
	v_mov_b32_e32 v95, v0
	v_mov_b32_e32 v108, v0
	v_mov_b32_e32 v109, v0
	v_mov_b32_e32 v110, v0
	v_mov_b32_e32 v111, v0
	v_mov_b32_e32 v112, v0
	v_mov_b32_e32 v113, v0
	v_mov_b32_e32 v114, v0
	v_mov_b32_e32 v115, v0
	v_mov_b32_e32 v124, v0
	v_mov_b32_e32 v125, v0
	v_mov_b32_e32 v126, v0
	v_mov_b32_e32 v127, v0
	v_mov_b32_e32 v128, v0
	v_mov_b32_e32 v129, v0
	v_mov_b32_e32 v130, v0
	v_mov_b32_e32 v131, v0
	.p2align 6
	s_nop 0
	s_nop 0
	s_nop 0
	s_nop 0
	s_nop 0
	s_nop 0
	s_nop 0
	s_nop 0
